# stagger the two batch domains: domain 1 sleeps ~10us (3 x s_sleep 100) before its S5-output/attention phase so its memory-bound epilogues run beside domain 0 MFMA loops; attention epilogue 16-byte acc
# speedup vs baseline: 1.0299x; 1.0149x over previous
; #define PROBE_BEGIN(id) unsigned long long pb_t0_##id = 0; if (PROBE_SEC == (id)) pb_t0_##id = __builtin_amdgcn_s_memrealtime();
; #define PROBE_END(id) if (PROBE_SEC == (id)) { const unsigned long long pb_t1_ = __builtin_amdgcn_s_memrealtime(), pb_dt_ = pb_t1_ - pb_t0_##id; while (__builtin_amdgcn_s_memrealtime() - pb_t1_ < pb_dt_) __builtin_amdgcn_s_sleep(4); }
; __global__ void __launch_bounds__(NWAVES * 64, 2) hybrid_fwd(Args args) {
;     ...
;     if (IN(2)) { PROBE_BEGIN(23) p3_ssm_out(F); PROBE_END(23)
;         if (s3bar) seam_arrive(s3bar, bar.x, F.MISC + 10);
;         PROBE_BEGIN(22) p2_mix(F, 0); PROBE_END(22)
.LBB0_497:
	s_cmp_lg_u32 s10, 1
	s_cbranch_scc1 .Ldly_skip1
	s_mov_b32 s0, 3
.Ldly_loop1:
	s_sleep 100
	s_sub_u32 s0, s0, 1
	s_cmp_lg_u32 s0, 0
	s_cbranch_scc1 .Ldly_loop1

; __device__ __forceinline__ unsigned cvt_pk_bf16(float lo, float hi) { unsigned r; asm volatile("v_cvt_pk_bf16_f32 %0, %1, %2" : "=v"(r) : "v"(lo), "v"(hi)); return r; }
; __device__ __forceinline__ float bflo(unsigned w) { return __uint_as_float(w << 16); }
; __device__ __forceinline__ float bfhi(unsigned w) { return __uint_as_float(w & 0xffff0000u); }
; __device__ __forceinline__ float fexp2(float x) { return __builtin_amdgcn_exp2f(x); }
; __device__ __forceinline__ float half_swap_sum(float v) { const auto rr = __builtin_amdgcn_permlane32_swap(__float_as_uint(v), __float_as_uint(v), false, false); return __uint_as_float(rr[0]) + __uint_as_float(rr[1]); }
; __device__ __forceinline__ void attn_compute(Frame& F, int id) {
;     ...
; #pragma unroll
;     for (int qb = 0; qb < 2; ++qb) {
;         const float mq = qb ? m1 : m0; float lt = half_swap_sum(qb ? l1 : l0); lt += fexp2(sk - mq);
;         const float inv = 1.0f / lt; const size_t tok = tok0 + 32 * qb;
; #pragma unroll
;         for (int dh = 0; dh < 2; ++dh)
; #pragma unroll
;             for (int gq = 0; gq < 4; ++gq) {
;                 const int d = 32 * dh + 8 * gq + 4 * hh;
;                 const v2u z = *(const v2u*)(ZA + tok * 512 + h * 64 + d);
;                 const f32x16& o = qb ? O1[dh] : O0[dh];
;                 v2u w; w.x = pg8::cvt_pk_bf16(o[4 * gq + 0] * inv * bflo(z.x), o[4 * gq + 1] * inv * bfhi(z.x));
;                 w.y = pg8::cvt_pk_bf16(o[4 * gq + 2] * inv * bflo(z.y), o[4 * gq + 3] * inv * bfhi(z.y));
;                 *(v2u*)(A5 + tok * 1024 + h * 64 + d) = w;
.LBB0_544:
	s_lshl_b32 s14, s22, 1
	s_add_u32 s4, s39, s14
	s_addc_u32 s5, s40, 0
	s_add_u32 s22, s37, s14
	s_addc_u32 s23, s38, 0
	v_mov_b32_e32 v203, v2
	v_and_b32_e32 v12, 32, v0
	v_mov_b32_e32 v13, 0
	v_lshrrev_b32_e32 v12, 2, v12
	v_lshl_add_u64 v[4:5], s[4:5], 0, v[206:207]
	v_lshl_add_u64 v[4:5], v[4:5], 0, v[202:203]
	v_lshl_add_u64 v[4:5], v[4:5], 0, v[12:13]
	global_load_dwordx4 v[82:85], v[4:5], off
	global_load_dwordx4 v[86:89], v[4:5], off offset:32
	global_load_dwordx4 v[90:93], v[4:5], off offset:64
	global_load_dwordx4 v[94:97], v[4:5], off offset:96
	v_lshlrev_b64 v[10:11], 11, v[204:205]
	v_or_b32_e32 v204, 32, v204
	v_lshlrev_b64 v[8:9], 10, v[204:205]
	v_lshl_add_u64 v[8:9], s[4:5], 0, v[8:9]
	v_lshl_add_u64 v[8:9], v[8:9], 0, v[202:203]
	v_lshl_add_u64 v[8:9], v[8:9], 0, v[12:13]
	global_load_dwordx4 v[98:101], v[8:9], off
	global_load_dwordx4 v[102:105], v[8:9], off offset:32
	global_load_dwordx4 v[106:109], v[8:9], off offset:64
	global_load_dwordx4 v[110:113], v[8:9], off offset:96
	v_lshl_add_u64 v[10:11], s[22:23], 0, v[10:11]
	v_lshl_add_u64 v[10:11], v[10:11], 0, v[202:203]
	v_lshl_add_u64 v[10:11], v[10:11], 0, v[12:13]
	v_lshlrev_b64 v[16:17], 11, v[204:205]
	v_lshl_add_u64 v[16:17], s[22:23], 0, v[16:17]
	v_lshl_add_u64 v[16:17], v[16:17], 0, v[202:203]
	v_lshl_add_u64 v[16:17], v[16:17], 0, v[12:13]
	s_mov_b32 s33, s44
	v_sub_f32_e32 v8, v244, v249
	v_exp_f32_e32 v8, v8
	v_mov_b32_e32 v3, v246
	s_nop 1
	v_permlane32_swap_b32_e32 v246, v3
	v_add_f32_e32 v3, v246, v3
	v_add_f32_e32 v3, v8, v3
	v_div_scale_f32 v8, vcc, v3, v3, 1.0
	v_rcp_f32_e32 v9, v8
	v_div_scale_f32 v12, vcc, 1.0, v3, 1.0
	v_fma_f32 v13, -v8, v9, 1.0
	v_fmac_f32_e32 v9, v13, v9
	v_mul_f32_e32 v13, v12, v9
	v_fma_f32 v14, -v8, v13, v12
	v_fmac_f32_e32 v13, v14, v9
	v_fma_f32 v8, -v8, v13, v12
	v_div_fmas_f32 v8, v8, v9, v13
	v_div_fixup_f32 v3, v8, v3, 1.0
	s_waitcnt vmcnt(7)
	v_permlane32_swap_b32_e32 v82, v84
	v_permlane32_swap_b32_e32 v83, v85
	v_mul_f32_e32 v12, v66, v3
	v_mul_f32_e32 v13, v67, v3
	v_mul_f32_e32 v14, v68, v3
	v_mul_f32_e32 v15, v69, v3
	v_lshlrev_b32_e32 v4, 16, v82
	v_and_b32_e32 v5, 0xffff0000, v82
	v_lshlrev_b32_e32 v6, 16, v83
	v_and_b32_e32 v7, 0xffff0000, v83
	v_mul_f32_e32 v4, v12, v4
	v_mul_f32_e32 v5, v13, v5
	v_mul_f32_e32 v6, v14, v6
	v_mul_f32_e32 v7, v15, v7
	v_cvt_pk_bf16_f32 v82, v4, v5
	v_cvt_pk_bf16_f32 v83, v6, v7
	v_mul_f32_e32 v12, v70, v3
	v_mul_f32_e32 v13, v71, v3
	v_mul_f32_e32 v14, v72, v3
	v_mul_f32_e32 v15, v73, v3
	v_lshlrev_b32_e32 v4, 16, v84
	v_and_b32_e32 v5, 0xffff0000, v84
	v_lshlrev_b32_e32 v6, 16, v85
	v_and_b32_e32 v7, 0xffff0000, v85
	v_mul_f32_e32 v4, v12, v4
	v_mul_f32_e32 v5, v13, v5
	v_mul_f32_e32 v6, v14, v6
	v_mul_f32_e32 v7, v15, v7
	v_cvt_pk_bf16_f32 v84, v4, v5
	v_cvt_pk_bf16_f32 v85, v6, v7
	s_nop 1
	v_permlane32_swap_b32_e32 v82, v84
	v_permlane32_swap_b32_e32 v83, v85
	global_store_dwordx4 v[10:11], v[82:85], off
	s_waitcnt vmcnt(7)
	v_permlane32_swap_b32_e32 v86, v88
	v_permlane32_swap_b32_e32 v87, v89
	v_mul_f32_e32 v12, v74, v3
	v_mul_f32_e32 v13, v75, v3
	v_mul_f32_e32 v14, v76, v3
	v_mul_f32_e32 v15, v77, v3
	v_lshlrev_b32_e32 v4, 16, v86
	v_and_b32_e32 v5, 0xffff0000, v86
	v_lshlrev_b32_e32 v6, 16, v87
	v_and_b32_e32 v7, 0xffff0000, v87
	v_mul_f32_e32 v4, v12, v4
	v_mul_f32_e32 v5, v13, v5
	v_mul_f32_e32 v6, v14, v6
	v_mul_f32_e32 v7, v15, v7
	v_cvt_pk_bf16_f32 v86, v4, v5
	v_cvt_pk_bf16_f32 v87, v6, v7
	v_mul_f32_e32 v12, v78, v3
	v_mul_f32_e32 v13, v79, v3
	v_mul_f32_e32 v14, v80, v3
	v_mul_f32_e32 v15, v81, v3
	v_lshlrev_b32_e32 v4, 16, v88
	v_and_b32_e32 v5, 0xffff0000, v88
	v_lshlrev_b32_e32 v6, 16, v89
	v_and_b32_e32 v7, 0xffff0000, v89
	v_mul_f32_e32 v4, v12, v4
	v_mul_f32_e32 v5, v13, v5
	v_mul_f32_e32 v6, v14, v6
	v_mul_f32_e32 v7, v15, v7
	v_cvt_pk_bf16_f32 v88, v4, v5
	v_cvt_pk_bf16_f32 v89, v6, v7
	s_nop 1
	v_permlane32_swap_b32_e32 v86, v88
	v_permlane32_swap_b32_e32 v87, v89
	global_store_dwordx4 v[10:11], v[86:89], off offset:32
	s_waitcnt vmcnt(7)
	v_permlane32_swap_b32_e32 v90, v92
	v_permlane32_swap_b32_e32 v91, v93
	v_mul_f32_e32 v12, v50, v3
	v_mul_f32_e32 v13, v51, v3
	v_mul_f32_e32 v14, v52, v3
	v_mul_f32_e32 v15, v53, v3
	v_lshlrev_b32_e32 v4, 16, v90
	v_and_b32_e32 v5, 0xffff0000, v90
	v_lshlrev_b32_e32 v6, 16, v91
	v_and_b32_e32 v7, 0xffff0000, v91
	v_mul_f32_e32 v4, v12, v4
	v_mul_f32_e32 v5, v13, v5
	v_mul_f32_e32 v6, v14, v6
	v_mul_f32_e32 v7, v15, v7
	v_cvt_pk_bf16_f32 v90, v4, v5
	v_cvt_pk_bf16_f32 v91, v6, v7
	v_mul_f32_e32 v12, v54, v3
	v_mul_f32_e32 v13, v55, v3
	v_mul_f32_e32 v14, v56, v3
	v_mul_f32_e32 v15, v57, v3
	v_lshlrev_b32_e32 v4, 16, v92
	v_and_b32_e32 v5, 0xffff0000, v92
	v_lshlrev_b32_e32 v6, 16, v93
	v_and_b32_e32 v7, 0xffff0000, v93
	v_mul_f32_e32 v4, v12, v4
	v_mul_f32_e32 v5, v13, v5
	v_mul_f32_e32 v6, v14, v6
	v_mul_f32_e32 v7, v15, v7
	v_cvt_pk_bf16_f32 v92, v4, v5
	v_cvt_pk_bf16_f32 v93, v6, v7
	s_nop 1
	v_permlane32_swap_b32_e32 v90, v92
	v_permlane32_swap_b32_e32 v91, v93
	global_store_dwordx4 v[10:11], v[90:93], off offset:64
	s_waitcnt vmcnt(7)
; __device__ __forceinline__ unsigned cvt_pk_bf16(float lo, float hi) { unsigned r; asm volatile("v_cvt_pk_bf16_f32 %0, %1, %2" : "=v"(r) : "v"(lo), "v"(hi)); return r; }
; __device__ __forceinline__ float bflo(unsigned w) { return __uint_as_float(w << 16); }
; __device__ __forceinline__ float bfhi(unsigned w) { return __uint_as_float(w & 0xffff0000u); }
; __device__ __forceinline__ float fexp2(float x) { return __builtin_amdgcn_exp2f(x); }
; __device__ __forceinline__ float half_swap_sum(float v) { const auto rr = __builtin_amdgcn_permlane32_swap(__float_as_uint(v), __float_as_uint(v), false, false); return __uint_as_float(rr[0]) + __uint_as_float(rr[1]); }
; __device__ __forceinline__ void attn_compute(Frame& F, int id) {
;     ...
; #pragma unroll
;     for (int qb = 0; qb < 2; ++qb) {
;         const float mq = qb ? m1 : m0; float lt = half_swap_sum(qb ? l1 : l0); lt += fexp2(sk - mq);
;         const float inv = 1.0f / lt; const size_t tok = tok0 + 32 * qb;
; #pragma unroll
;         for (int dh = 0; dh < 2; ++dh)
; #pragma unroll
;             for (int gq = 0; gq < 4; ++gq) {
;                 const int d = 32 * dh + 8 * gq + 4 * hh;
;                 const v2u z = *(const v2u*)(ZA + tok * 512 + h * 64 + d);
;                 const f32x16& o = qb ? O1[dh] : O0[dh];
;                 v2u w; w.x = pg8::cvt_pk_bf16(o[4 * gq + 0] * inv * bflo(z.x), o[4 * gq + 1] * inv * bfhi(z.x));
;                 w.y = pg8::cvt_pk_bf16(o[4 * gq + 2] * inv * bflo(z.y), o[4 * gq + 3] * inv * bfhi(z.y));
;                 *(v2u*)(A5 + tok * 1024 + h * 64 + d) = w;
;             }
;     }
	v_permlane32_swap_b32_e32 v94, v96
	v_permlane32_swap_b32_e32 v95, v97
	v_mul_f32_e32 v12, v58, v3
	v_mul_f32_e32 v13, v59, v3
	v_mul_f32_e32 v14, v60, v3
	v_mul_f32_e32 v15, v61, v3
	v_lshlrev_b32_e32 v4, 16, v94
	v_and_b32_e32 v5, 0xffff0000, v94
	v_lshlrev_b32_e32 v6, 16, v95
	v_and_b32_e32 v7, 0xffff0000, v95
	v_mul_f32_e32 v4, v12, v4
	v_mul_f32_e32 v5, v13, v5
	v_mul_f32_e32 v6, v14, v6
	v_mul_f32_e32 v7, v15, v7
	v_cvt_pk_bf16_f32 v94, v4, v5
	v_cvt_pk_bf16_f32 v95, v6, v7
	v_mul_f32_e32 v12, v62, v3
	v_mul_f32_e32 v13, v63, v3
	v_mul_f32_e32 v14, v64, v3
	v_mul_f32_e32 v15, v65, v3
	v_lshlrev_b32_e32 v4, 16, v96
	v_and_b32_e32 v5, 0xffff0000, v96
	v_lshlrev_b32_e32 v6, 16, v97
	v_and_b32_e32 v7, 0xffff0000, v97
	v_mul_f32_e32 v4, v12, v4
	v_mul_f32_e32 v5, v13, v5
	v_mul_f32_e32 v6, v14, v6
	v_mul_f32_e32 v7, v15, v7
	v_cvt_pk_bf16_f32 v96, v4, v5
	v_cvt_pk_bf16_f32 v97, v6, v7
	s_nop 1
	v_permlane32_swap_b32_e32 v94, v96
	v_permlane32_swap_b32_e32 v95, v97
	global_store_dwordx4 v[10:11], v[94:97], off offset:96
	v_sub_f32_e32 v8, v244, v245
	v_exp_f32_e32 v8, v8
	v_mov_b32_e32 v3, v201
	s_nop 1
	v_permlane32_swap_b32_e32 v201, v3
	v_add_f32_e32 v3, v201, v3
	v_add_f32_e32 v3, v8, v3
	v_div_scale_f32 v8, vcc, v3, v3, 1.0
	v_rcp_f32_e32 v9, v8
	v_div_scale_f32 v12, vcc, 1.0, v3, 1.0
	v_fma_f32 v13, -v8, v9, 1.0
	v_fmac_f32_e32 v9, v13, v9
	v_mul_f32_e32 v13, v12, v9
	v_fma_f32 v14, -v8, v13, v12
	v_fmac_f32_e32 v13, v14, v9
	v_fma_f32 v8, -v8, v13, v12
	v_div_fmas_f32 v8, v8, v9, v13
	v_div_fixup_f32 v3, v8, v3, 1.0
	s_waitcnt vmcnt(7)
	v_permlane32_swap_b32_e32 v98, v100
	v_permlane32_swap_b32_e32 v99, v101
	v_mul_f32_e32 v12, v34, v3
	v_mul_f32_e32 v13, v35, v3
	v_mul_f32_e32 v14, v36, v3
	v_mul_f32_e32 v15, v37, v3
	v_lshlrev_b32_e32 v4, 16, v98
	v_and_b32_e32 v5, 0xffff0000, v98
	v_lshlrev_b32_e32 v6, 16, v99
	v_and_b32_e32 v7, 0xffff0000, v99
	v_mul_f32_e32 v4, v12, v4
	v_mul_f32_e32 v5, v13, v5
	v_mul_f32_e32 v6, v14, v6
	v_mul_f32_e32 v7, v15, v7
	v_cvt_pk_bf16_f32 v98, v4, v5
	v_cvt_pk_bf16_f32 v99, v6, v7
	v_mul_f32_e32 v12, v38, v3
	v_mul_f32_e32 v13, v39, v3
	v_mul_f32_e32 v14, v40, v3
	v_mul_f32_e32 v15, v41, v3
	v_lshlrev_b32_e32 v4, 16, v100
	v_and_b32_e32 v5, 0xffff0000, v100
	v_lshlrev_b32_e32 v6, 16, v101
	v_and_b32_e32 v7, 0xffff0000, v101
	v_mul_f32_e32 v4, v12, v4
	v_mul_f32_e32 v5, v13, v5
	v_mul_f32_e32 v6, v14, v6
	v_mul_f32_e32 v7, v15, v7
	v_cvt_pk_bf16_f32 v100, v4, v5
	v_cvt_pk_bf16_f32 v101, v6, v7
	s_nop 1
	v_permlane32_swap_b32_e32 v98, v100
	v_permlane32_swap_b32_e32 v99, v101
	global_store_dwordx4 v[16:17], v[98:101], off
	s_waitcnt vmcnt(7)
	v_permlane32_swap_b32_e32 v102, v104
	v_permlane32_swap_b32_e32 v103, v105
	v_mul_f32_e32 v12, v42, v3
	v_mul_f32_e32 v13, v43, v3
	v_mul_f32_e32 v14, v44, v3
	v_mul_f32_e32 v15, v45, v3
	v_lshlrev_b32_e32 v4, 16, v102
	v_and_b32_e32 v5, 0xffff0000, v102
	v_lshlrev_b32_e32 v6, 16, v103
	v_and_b32_e32 v7, 0xffff0000, v103
	v_mul_f32_e32 v4, v12, v4
	v_mul_f32_e32 v5, v13, v5
	v_mul_f32_e32 v6, v14, v6
	v_mul_f32_e32 v7, v15, v7
	v_cvt_pk_bf16_f32 v102, v4, v5
	v_cvt_pk_bf16_f32 v103, v6, v7
	v_mul_f32_e32 v12, v46, v3
	v_mul_f32_e32 v13, v47, v3
	v_mul_f32_e32 v14, v48, v3
	v_mul_f32_e32 v15, v49, v3
	v_lshlrev_b32_e32 v4, 16, v104
	v_and_b32_e32 v5, 0xffff0000, v104
	v_lshlrev_b32_e32 v6, 16, v105
	v_and_b32_e32 v7, 0xffff0000, v105
	v_mul_f32_e32 v4, v12, v4
	v_mul_f32_e32 v5, v13, v5
	v_mul_f32_e32 v6, v14, v6
	v_mul_f32_e32 v7, v15, v7
	v_cvt_pk_bf16_f32 v104, v4, v5
	v_cvt_pk_bf16_f32 v105, v6, v7
	s_nop 1
	v_permlane32_swap_b32_e32 v102, v104
	v_permlane32_swap_b32_e32 v103, v105
	global_store_dwordx4 v[16:17], v[102:105], off offset:32
	s_waitcnt vmcnt(7)
	v_permlane32_swap_b32_e32 v106, v108
	v_permlane32_swap_b32_e32 v107, v109
	v_mul_f32_e32 v12, v18, v3
	v_mul_f32_e32 v13, v19, v3
	v_mul_f32_e32 v14, v20, v3
	v_mul_f32_e32 v15, v21, v3
	v_lshlrev_b32_e32 v4, 16, v106
	v_and_b32_e32 v5, 0xffff0000, v106
	v_lshlrev_b32_e32 v6, 16, v107
	v_and_b32_e32 v7, 0xffff0000, v107
	v_mul_f32_e32 v4, v12, v4
	v_mul_f32_e32 v5, v13, v5
	v_mul_f32_e32 v6, v14, v6
	v_mul_f32_e32 v7, v15, v7
	v_cvt_pk_bf16_f32 v106, v4, v5
	v_cvt_pk_bf16_f32 v107, v6, v7
	v_mul_f32_e32 v12, v22, v3
	v_mul_f32_e32 v13, v23, v3
	v_mul_f32_e32 v14, v24, v3
	v_mul_f32_e32 v15, v25, v3
	v_lshlrev_b32_e32 v4, 16, v108
	v_and_b32_e32 v5, 0xffff0000, v108
	v_lshlrev_b32_e32 v6, 16, v109
	v_and_b32_e32 v7, 0xffff0000, v109
	v_mul_f32_e32 v4, v12, v4
	v_mul_f32_e32 v5, v13, v5
	v_mul_f32_e32 v6, v14, v6
	v_mul_f32_e32 v7, v15, v7
	v_cvt_pk_bf16_f32 v108, v4, v5
	v_cvt_pk_bf16_f32 v109, v6, v7
	s_nop 1
	v_permlane32_swap_b32_e32 v106, v108
	v_permlane32_swap_b32_e32 v107, v109
	global_store_dwordx4 v[16:17], v[106:109], off offset:64
	s_waitcnt vmcnt(7)
	v_permlane32_swap_b32_e32 v110, v112
	v_permlane32_swap_b32_e32 v111, v113
	v_mul_f32_e32 v12, v26, v3
	v_mul_f32_e32 v13, v27, v3
	v_mul_f32_e32 v14, v28, v3
	v_mul_f32_e32 v15, v29, v3
	v_lshlrev_b32_e32 v4, 16, v110
	v_and_b32_e32 v5, 0xffff0000, v110
	v_lshlrev_b32_e32 v6, 16, v111
	v_and_b32_e32 v7, 0xffff0000, v111
	v_mul_f32_e32 v4, v12, v4
	v_mul_f32_e32 v5, v13, v5
	v_mul_f32_e32 v6, v14, v6
	v_mul_f32_e32 v7, v15, v7
	v_cvt_pk_bf16_f32 v110, v4, v5
	v_cvt_pk_bf16_f32 v111, v6, v7
	v_mul_f32_e32 v12, v30, v3
	v_mul_f32_e32 v13, v31, v3
	v_mul_f32_e32 v14, v32, v3
	v_mul_f32_e32 v15, v33, v3
	v_lshlrev_b32_e32 v4, 16, v112
	v_and_b32_e32 v5, 0xffff0000, v112
	v_lshlrev_b32_e32 v6, 16, v113
	v_and_b32_e32 v7, 0xffff0000, v113
	v_mul_f32_e32 v4, v12, v4
	v_mul_f32_e32 v5, v13, v5
	v_mul_f32_e32 v6, v14, v6
	v_mul_f32_e32 v7, v15, v7
	v_cvt_pk_bf16_f32 v112, v4, v5
	v_cvt_pk_bf16_f32 v113, v6, v7
	s_nop 1
	v_permlane32_swap_b32_e32 v110, v112
	v_permlane32_swap_b32_e32 v111, v113
	global_store_dwordx4 v[16:17], v[110:113], off offset:96
	s_andn2_b64 vcc, exec, s[2:3]
	s_barrier
	s_cbranch_vccz .LBB0_580
